# attn: V staging thread map key=tid&63 chunk=tid>>6 (conflict-free transposing LDS writes) + rescheduled ks-loop
# speedup vs baseline: 1.0879x; 1.0173x over previous
; __device__ __forceinline__ void attn_phase(const Params& p, char* smem) {
;     ...
;     const bool stab = __any(bmax > 60.0f) != 0;
;     const bf16_t* kbase = Kg + (size_t)bh * TPB * 96;
;     const bf16_t* vbase = KVRAW + (size_t)b * TPB * 1024 + h * 128 + 64;
;     ...
;     uint4 rk0, rk1, rk2, rv0, rv1;
;     const int nkt = nkeys / KT;
;     rk0 = *(const uint4*)(kbase + kgo); rk1 = *(const uint4*)(kbase + kgo + 8); rk2 = *(const uint4*)(kbase + kgo + 16);
;     rv0 = *(const uint4*)(vbase + (size_t)vkey0 * 1024 + vch * 8); rv1 = *(const uint4*)(vbase + (size_t)(vkey0 + 64) * 1024 + vch * 8);
;     {
;       *(uint4*)(Ks + klo) = rk0; *(uint4*)(Ks + klo + 8) = rk1; *(uint4*)(Ks + klo + 16) = rk2;
;       vt_scatter(Vt + (vch * 8) * VLD + vkey0, VLD, rv0); vt_scatter(Vt + (vch * 8) * VLD + vkey0 + 64, VLD, rv1);
.LBB0_392:
	s_and_b64 vcc, exec, s[2:3]
	s_cbranch_vccz .LBB0_426
	v_mov_b32_e32 v0, v164
	s_mov_b32 s12, s82
	s_cmpk_gt_i32 s12, 0x10f
	s_cbranch_scc1 .LBB0_426
	s_load_dwordx2 s[44:45], s[0:1], 0xf0
	v_bfe_u32 v1, v0, 4, 2
	v_lshlrev_b32_e32 v2, 4, v1
	v_mov_b32_e32 v3, v167
	v_lshlrev_b32_e32 v166, 3, v1
	s_waitcnt lgkmcnt(0)
	v_lshl_add_u64 v[4:5], s[44:45], 0, v[2:3]
	v_and_b32_e32 v3, 64, v231
	v_xor_b32_e32 v1, 16, v231
	v_add_u32_e32 v3, 64, v3
	v_cmp_lt_i32_e32 vcc, v1, v3
	s_mov_b64 s[2:3], 0x7290000
	v_lshl_add_u64 v[180:181], v[4:5], 0, s[2:3]
	v_cndmask_b32_e32 v1, v231, v1, vcc
	v_lshlrev_b32_e32 v235, 2, v1
	v_xor_b32_e32 v1, 32, v231
	v_cmp_lt_i32_e32 vcc, v1, v3
	s_movk_i32 s2, 0x60
	v_and_b32_e32 v4, 3, v0
	v_cndmask_b32_e32 v1, v231, v1, vcc
	v_lshlrev_b32_e32 v236, 2, v1
	v_ashrrev_i32_e32 v1, 2, v0
	v_mul_lo_u32 v3, v1, s2
	v_mul_u32_u24_e32 v10, 24, v4
	v_mad_u32_u24 v4, v4, 24, v3
	v_and_b32_e32 v6, 63, v0
	v_lshrrev_b32_e32 v3, 3, v0
	s_movk_i32 s4, 0xd0
	v_ashrrev_i32_e32 v7, 31, v6
	v_and_b32_e32 v8, 56, v3
	v_mul_lo_u32 v1, v1, s4
	v_lshlrev_b32_e32 v3, 1, v10
	v_lshlrev_b64 v[182:183], 11, v[6:7]
	s_mov_b64 s[2:3], 0x20000
	v_add3_u32 v237, 0, v1, v3
	v_mul_u32_u24_e32 v1, 0x110, v8
	v_lshlrev_b32_e32 v3, 1, v6
	v_and_b32_e32 v9, 15, v0
	v_and_b32_e32 v171, 0xffffffc0, v0
	v_ashrrev_i32_e32 v5, 31, v4
	v_lshl_add_u64 v[184:185], v[182:183], 0, s[2:3]
	v_add3_u32 v238, 0, v1, v3
	v_and_b32_e32 v239, 0xffffffcf, v0
	v_lshl_add_u64 v[0:1], s[44:45], 0, v[166:167]
	s_mov_b64 s[2:3], 0x5190000
	v_lshl_add_u64 v[186:187], v[0:1], 0, s[2:3]
	v_lshl_add_u64 v[0:1], v[4:5], 1, s[44:45]
	s_mov_b64 s[2:3], 0x8b50000
	v_lshl_add_u64 v[188:189], v[0:1], 0, s[2:3]
	s_add_u32 s13, s44, 0x115d0900
	s_movk_i32 s2, 0x110
	v_ashrrev_i32_e32 v179, 31, v171
	v_or_b32_e32 v178, v171, v9
	s_addc_u32 s14, s45, 0
	v_mad_u32_u24 v240, v9, s2, v166
	v_mad_u32_u24 v241, v9, s4, v2
	v_lshlrev_b32_e32 v166, 1, v8
	s_branch .LBB0_396
